# SSD: DPP prefix sums + hand-written W (decay-mask) stage
# speedup vs baseline: 1.0151x; 1.0151x over previous
; __device__ __forceinline__ void ssd_item(CArgs a, int layer, int item, LAS unsigned char* lds) {
;     ...
;         float etot;
;         {
;             float tot = 0.f, pre = 0.f;
;             if (tid < 128) {
;                 const float mine = v_dA[tid];
;                 float sc = mine;
; #pragma unroll
;                 for (int o = 1; o < 64; o <<= 1) { const float tt = __shfl_up(sc, o); sc += (lane >= o) ? tt : 0.f; }
;                 const float w0 = wave_sum(v_dA[lane]), w1 = wave_sum(v_dA[64 + lane]);
;                 tot = w0 + w1; pre = sc + (wid == 1 ? w0 : 0.f);
;                 if (dir) pre = tot - pre + mine;
;                 v_cs[tid] = pre; v_ecs[tid] = __builtin_amdgcn_exp2f(pre); v_wgt[tid] = dtv * __builtin_amdgcn_exp2f(tot - pre); v_dt[tid] = dtv;
;                 if (tid == 0) vec[640] = __builtin_amdgcn_exp2f(tot);
;             }
;         }
.LBB0_200:
	v_and_b32_e32 v126, 63, v123
	s_ashr_i32 s91, s34, 6
	s_and_saveexec_b64 s[26:27], vcc
	s_cbranch_execz .LBB0_203
	v_lshlrev_b32_e32 v20, 2, v123
	s_add_i32 s2, 0, 0x22000
	v_add_u32_e32 v0, s2, v20
	ds_read_b32 v21, v0
	v_lshl_add_u32 v18, v126, 2, s2
	ds_read2st64_b32 v[18:19], v18 offset1:1
	s_waitcnt lgkmcnt(0)
	s_nop 1
	v_add_f32_dpp v18, v18, v18 row_shr:1 row_mask:0xf bank_mask:0xf bound_ctrl:0
	v_add_f32_dpp v19, v19, v19 row_shr:1 row_mask:0xf bank_mask:0xf bound_ctrl:0
	s_nop 1
	v_add_f32_dpp v18, v18, v18 row_shr:2 row_mask:0xf bank_mask:0xf bound_ctrl:0
	v_add_f32_dpp v19, v19, v19 row_shr:2 row_mask:0xf bank_mask:0xf bound_ctrl:0
	s_nop 1
	v_add_f32_dpp v18, v18, v18 row_shr:4 row_mask:0xf bank_mask:0xf bound_ctrl:0
	v_add_f32_dpp v19, v19, v19 row_shr:4 row_mask:0xf bank_mask:0xf bound_ctrl:0
	s_nop 1
	v_add_f32_dpp v18, v18, v18 row_shr:8 row_mask:0xf bank_mask:0xf bound_ctrl:0
	v_add_f32_dpp v19, v19, v19 row_shr:8 row_mask:0xf bank_mask:0xf bound_ctrl:0
	s_nop 1
	v_add_f32_dpp v18, v18, v18 row_bcast:15 row_mask:0xa bank_mask:0xf
	v_add_f32_dpp v19, v19, v19 row_bcast:15 row_mask:0xa bank_mask:0xf
	s_nop 1
	v_add_f32_dpp v18, v18, v18 row_bcast:31 row_mask:0xc bank_mask:0xf
	v_add_f32_dpp v19, v19, v19 row_bcast:31 row_mask:0xc bank_mask:0xf
	s_nop 1
	s_nop 1
	v_readlane_b32 s2, v18, 63
	v_readlane_b32 s3, v19, 63
	s_cmp_eq_u32 s91, 1
	s_cselect_b64 vcc, -1, 0
	s_nop 1
	v_cndmask_b32_e32 v22, v18, v19, vcc
	v_mov_b32_e32 v18, s2
	v_mov_b32_e32 v0, s3
	v_add_f32_e32 v0, v18, v0
	v_cndmask_b32_e32 v18, 0, v18, vcc
	v_add_f32_e32 v18, v22, v18
	v_sub_f32_e32 v19, v0, v18
	v_add_f32_e32 v19, v21, v19
	v_cndmask_b32_e64 v18, v19, v18, s[40:41]
	v_add_u32_e32 v19, 0, v20
	v_add_u32_e32 v20, 0x22200, v19
	ds_write_b32 v20, v18
	v_exp_f32_e32 v20, v18
	v_sub_f32_e32 v18, v0, v18
	v_exp_f32_e32 v18, v18
	v_add_u32_e32 v21, 0x22400, v19
	ds_write_b32 v21, v20
	v_add_u32_e32 v20, 0x22600, v19
	v_mul_f32_e32 v18, v192, v18
	ds_write_b32 v20, v18
	v_add_u32_e32 v18, 0x22800, v19
	v_cmp_eq_u32_e32 vcc, 0, v123
	ds_write_b32 v18, v192
	s_and_b64 exec, exec, vcc
	s_cbranch_execz .LBB0_203
	v_exp_f32_e32 v0, v0
	v_mov_b32_e32 v18, s76
	ds_write_b32 v18, v0

; #define LAS __attribute__((address_space(3)))
; #define MFMA32(a, b, c) __builtin_amdgcn_mfma_f32_32x32x16_bf16((a), (b), (c), 0, 0, 0)
; __device__ __forceinline__ int crow(int r, int hi) { return (r & 3) + 8 * (r >> 2) + 4 * hi; }
; __device__ __forceinline__ void ssd_item(CArgs a, int layer, int item, LAS unsigned char* lds) {
;     ...
;         f32x16 G0, G1;
; #pragma unroll
;         for (int r = 0; r < 16; ++r) { G0[r] = 0.f; G1[r] = 0.f; }
; #pragma unroll
;         for (int ks = 0; ks < 8; ++ks) {
;             const bf16x8 af = *(const LAS bf16x8*)(Cm + (32 * gi + r32) * SS_LD + 16 * ks + 8 * hi);
;             const bf16x8 b0 = *(const LAS bf16x8*)(Bw + (32 * gj0 + r32) * SS_LD + 16 * ks + 8 * hi);
;             const bf16x8 b1 = *(const LAS bf16x8*)(Bw + (32 * (gj0 + 1) + r32) * SS_LD + 16 * ks + 8 * hi);
;             G0 = MFMA32(af, b0, G0); G1 = MFMA32(af, b1, G1);
;         }
;         __syncthreads();
;         {
; #pragma unroll
;             for (int r = 0; r < 16; ++r) Sacc[r] *= etot;
; #pragma unroll
;             for (int ks = 0; ks < 8; ++ks) {
;                 const bf16x8 xa = *(const LAS bf16x8*)(Xt + (32 * si + r32) * SS_LD + 16 * ks + 8 * hi);
;                 const bf16x8 bb = *(const LAS bf16x8*)(Bt + (32 * sj + r32) * SS_LD + 16 * ks + 8 * hi);
;                 Sacc = MFMA32(xa, bb, Sacc);
;             }
;             const int s0i = 32 * gj0 + r32, s1i = s0i + 32;
;             const float cs0 = v_cs[s0i], cs1 = v_cs[s1i], d0 = v_dt[s0i], d1 = v_dt[s1i];
; #pragma unroll
;             for (int r = 0; r < 16; ++r) {
;                 const int l = 32 * gi + crow(r, hi); const float csl = v_cs[l];
.LBB0_207:
	s_and_b32 s27, s91, 1
	s_and_b32 s2, s91, 3
	s_add_i32 s3, s10, 1
	s_and_b64 s[42:43], s[40:41], exec
	s_cselect_b32 s3, s90, s3
	s_ashr_i32 s42, s34, 2
	v_mov_b32_e32 v18, s42
	v_lshrrev_b32_e32 v196, 5, v126
	v_bfi_b32 v18, s39, v18, v123
	v_mul_lo_u32 v18, v18, s84
	v_lshlrev_b32_e32 v194, 4, v196
	v_add3_u32 v193, 0, v18, v194
	s_waitcnt lgkmcnt(0)
	s_barrier
	ds_read_b128 v[34:37], v193
	v_and_b32_e32 v0, 31, v123
	v_lshl_or_b32 v195, s27, 6, v0
	v_mul_u32_u24_e32 v18, 0x110, v195
	v_add3_u32 v128, 0, v18, v194
	ds_read_b128 v[18:21], v128 offset:34816
	ds_read_b128 v[106:109], v193 offset:32
	ds_read_b128 v[38:41], v128 offset:34848
	s_waitcnt lgkmcnt(2)
	v_mfma_f32_32x32x16_bf16 v[18:33], v[34:37], v[18:21], 0
	v_mul_f32_e64 v16, v16, v122
	v_mul_f32_e64 v17, v17, v122
	v_mul_f32_e64 v14, v14, v122
	v_mul_f32_e64 v15, v15, v122
	v_mul_f32_e64 v12, v12, v122
	v_mul_f32_e64 v13, v13, v122
	v_pk_mul_f32 v[10:11], v[10:11], v[122:123] op_sel_hi:[1,0]
	v_pk_mul_f32 v[8:9], v[8:9], v[122:123] op_sel_hi:[1,0]
	v_pk_mul_f32 v[6:7], v[6:7], v[122:123] op_sel_hi:[1,0]
	v_pk_mul_f32 v[4:5], v[4:5], v[122:123] op_sel_hi:[1,0]
	s_waitcnt lgkmcnt(0)
	v_mfma_f32_32x32x16_bf16 v[18:33], v[106:109], v[38:41], v[18:33]
	ds_read_b128 v[38:41], v128 offset:43520
	ds_read_b128 v[110:113], v128 offset:43552
	ds_read_b128 v[114:117], v193 offset:64
	ds_read_b128 v[118:121], v128 offset:34880
	ds_read_b128 v[124:127], v128 offset:34912
	ds_read_b128 v[186:189], v193 offset:96
	ds_read_b128 v[182:185], v193 offset:128
	v_pk_mul_f32 v[2:3], v[2:3], v[122:123] op_sel_hi:[1,0]
	s_ashr_i32 s34, s34, 3
	v_mov_b32_e32 v129, s34
	s_and_b32 s43, s42, 0xffffffe0
	s_waitcnt lgkmcnt(3)
	v_mfma_f32_32x32x16_bf16 v[18:33], v[114:117], v[118:121], v[18:33]
	ds_read_b128 v[118:121], v128 offset:34944
	s_add_i32 s42, 0, 0x22200
	s_add_i32 s44, 0, 0x22800
	s_andn2_b32 s34, s34, 31
	s_add_i32 s10, s10, -1
	s_waitcnt lgkmcnt(2)
	v_mfma_f32_32x32x16_bf16 v[18:33], v[186:189], v[124:127], v[18:33]
	ds_read_b128 v[124:127], v128 offset:34976
	ds_read_b128 v[178:181], v193 offset:160
	ds_read_b128 v[200:203], v193 offset:192
	v_mfma_f32_32x32x16_bf16 v[34:49], v[34:37], v[38:41], 0
	s_waitcnt lgkmcnt(3)
	v_mfma_f32_32x32x16_bf16 v[18:33], v[182:185], v[118:121], v[18:33]
	v_lshl_or_b32 v118, s2, 5, v0
	v_mul_u32_u24_e32 v122, 0x110, v118
	ds_read_b128 v[118:121], v128 offset:35008
	v_add3_u32 v197, s77, v122, v194
	v_bfi_b32 v122, s39, v129, v123
	v_mul_lo_u32 v122, v122, s84
	v_add3_u32 v198, s38, v122, v194
	s_waitcnt lgkmcnt(2)
	v_mfma_f32_32x32x16_bf16 v[18:33], v[178:181], v[124:127], v[18:33]
	ds_read_b128 v[124:127], v128 offset:35040
	ds_read_b128 v[170:173], v193 offset:224
	s_lshl_b32 s2, s2, 6
	s_add_i32 s2, s75, s2
	v_mfma_f32_32x32x16_bf16 v[34:49], v[106:109], v[110:113], v[34:49]
	s_waitcnt lgkmcnt(2)
	v_mfma_f32_32x32x16_bf16 v[18:33], v[200:203], v[118:121], v[18:33]
	ds_read_b128 v[118:121], v128 offset:43584
	ds_read_b128 v[204:207], v128 offset:43616
	ds_read_b128 v[208:211], v128 offset:43648
	ds_read_b128 v[212:215], v128 offset:43680
	ds_read_b128 v[216:219], v128 offset:43712
	ds_read_b128 v[174:177], v128 offset:43744
	s_waitcnt lgkmcnt(0)
	s_barrier
	ds_read_b128 v[162:165], v198
	ds_read_b128 v[154:157], v198 offset:32
	v_mfma_f32_32x32x16_bf16 v[34:49], v[114:117], v[118:121], v[34:49]
	v_mfma_f32_32x32x16_bf16 v[34:49], v[186:189], v[204:207], v[34:49]
	v_mfma_f32_32x32x16_bf16 v[34:49], v[182:185], v[208:211], v[34:49]
	v_lshlrev_b32_e32 v183, 2, v196
	v_or_b32_e32 v182, s43, v183
	v_lshlrev_b32_e32 v184, 2, v182
	v_mfma_f32_32x32x16_bf16 v[34:49], v[178:181], v[212:215], v[34:49]
	v_mfma_f32_32x32x16_bf16 v[34:49], v[200:203], v[216:219], v[34:49]
	v_mfma_f32_32x32x16_bf16 v[18:33], v[170:173], v[124:127], v[18:33]
	ds_read_b128 v[166:169], v197
	ds_read_b128 v[158:161], v197 offset:32
	ds_read_b128 v[146:149], v198 offset:64
	ds_read_b128 v[138:141], v198 offset:96
	ds_read_b128 v[150:153], v197 offset:64
	ds_read_b128 v[142:145], v197 offset:96
	ds_read_b128 v[130:133], v198 offset:128
	ds_read_b128 v[122:125], v198 offset:160
	ds_read_b128 v[134:137], v197 offset:128
	ds_read_b128 v[126:129], v197 offset:160
	ds_read_b128 v[114:117], v198 offset:192
	ds_read_b128 v[106:109], v198 offset:224
	ds_read_b128 v[118:121], v197 offset:192
	ds_read_b128 v[110:113], v197 offset:224
	v_or_b32_e32 v198, 32, v195
	v_mfma_f32_32x32x16_bf16 v[34:49], v[170:173], v[174:177], v[34:49]
	v_readfirstlane_b32 s98, v244
	v_and_b32_e32 v240, 31, v244
	v_bfe_u32 v241, v244, 5, 1
	s_lshr_b32 s98, s98, 6
	s_lshr_b32 s99, s98, 1
	s_lshl_b32 s99, s99, 5
	s_and_b32 s98, s98, 1
	s_lshl_b32 s98, s98, 6
	v_add_u32_e32 v240, s98, v240
	v_lshl_add_u32 v241, v241, 2, s99
	v_sub_u32_e32 v221, v240, v241
	v_add_u32_e32 v222, 32, v221
	v_mul_u32_u24_e32 v220, 0x110, v241
	v_lshl_add_u32 v220, v240, 1, v220
	v_lshlrev_b32_e32 v240, 2, v240
	v_add_u32_e32 v240, 0x22200, v240
	v_lshlrev_b32_e32 v241, 2, v241
	v_add_u32_e32 v241, 0x22200, v241
	ds_read_b32 v223, v240
	ds_read_b32 v224, v240 offset:128
	ds_read_b32 v225, v240 offset:1536
	ds_read_b32 v226, v240 offset:1664
	ds_read_b128 v[232:235], v241
	ds_read_b128 v[236:239], v241 offset:32
	ds_read_b128 v[172:175], v241 offset:64
	ds_read_b128 v[178:181], v241 offset:96
	s_waitcnt lgkmcnt(0)
	s_and_b64 vcc, exec, s[40:41]
	s_cbranch_vccz .Lssd_w_bwd
; #define LAS __attribute__((address_space(3)))
; __device__ __forceinline__ unsigned short f2bf(float f) { return (unsigned short)(cvt_pk_bf16(f, 0.f) & 0xffffu); }
; #define MFMA32(a, b, c) __builtin_amdgcn_mfma_f32_32x32x16_bf16((a), (b), (c), 0, 0, 0)
; __device__ __forceinline__ int crow(int r, int hi) { return (r & 3) + 8 * (r >> 2) + 4 * hi; }
; __device__ __forceinline__ void ssd_item(CArgs a, int layer, int item, LAS unsigned char* lds) {
;     ...
;         {
; #pragma unroll
;             for (int r = 0; r < 16; ++r) Sacc[r] *= etot;
; #pragma unroll
;             for (int ks = 0; ks < 8; ++ks) {
;                 const bf16x8 xa = *(const LAS bf16x8*)(Xt + (32 * si + r32) * SS_LD + 16 * ks + 8 * hi);
;                 const bf16x8 bb = *(const LAS bf16x8*)(Bt + (32 * sj + r32) * SS_LD + 16 * ks + 8 * hi);
;                 Sacc = MFMA32(xa, bb, Sacc);
;             }
;             const int s0i = 32 * gj0 + r32, s1i = s0i + 32;
;             const float cs0 = v_cs[s0i], cs1 = v_cs[s1i], d0 = v_dt[s0i], d1 = v_dt[s1i];
; #pragma unroll
;             for (int r = 0; r < 16; ++r) {
;                 const int l = 32 * gi + crow(r, hi); const float csl = v_cs[l];
;                 const bool ok0 = dir ? (s0i >= l) : (s0i <= l), ok1 = dir ? (s1i >= l) : (s1i <= l);
;                 const float w0 = ok0 ? G0[r] * __builtin_amdgcn_exp2f(csl - cs0) * d0 : 0.f;
;                 const float w1 = ok1 ? G1[r] * __builtin_amdgcn_exp2f(csl - cs1) * d1 : 0.f;
;                 Bw[l * SS_LD + s0i] = f2bf(w0); Bw[l * SS_LD + s1i] = f2bf(w1);
;             }
	v_mfma_f32_32x32x16_bf16 v[2:17], v[162:165], v[166:169], v[2:17]
	v_sub_f32_e32 v227, v232, v223
	v_sub_f32_e32 v228, v232, v224
	v_exp_f32_e32 v227, v227
	v_exp_f32_e32 v228, v228
	v_cmp_ge_i32_e32 vcc, 0, v221
	v_mul_f32_e32 v227, v18, v227
	v_mul_f32_e32 v227, v225, v227
	v_cndmask_b32_e32 v227, 0, v227, vcc
	v_cmp_ge_i32_e32 vcc, 0, v222
	v_mul_f32_e32 v228, v34, v228
	v_mul_f32_e32 v228, v226, v228
	v_cndmask_b32_e32 v228, 0, v228, vcc
	v_cvt_pk_bf16_f32 v227, v227, v228
	ds_write_b16 v220, v227 offset:34816
	ds_write_b16_d16_hi v220, v227 offset:34880
	v_sub_f32_e32 v229, v233, v223
	v_sub_f32_e32 v230, v233, v224
	v_exp_f32_e32 v229, v229
	v_exp_f32_e32 v230, v230
	v_cmp_ge_i32_e32 vcc, 1, v221
	v_mul_f32_e32 v229, v19, v229
	v_mul_f32_e32 v229, v225, v229
	v_cndmask_b32_e32 v229, 0, v229, vcc
	v_cmp_ge_i32_e32 vcc, 1, v222
	v_mul_f32_e32 v230, v35, v230
	v_mul_f32_e32 v230, v226, v230
	v_cndmask_b32_e32 v230, 0, v230, vcc
	v_cvt_pk_bf16_f32 v229, v229, v230
	ds_write_b16 v220, v229 offset:35088
	ds_write_b16_d16_hi v220, v229 offset:35152
	v_mfma_f32_32x32x16_bf16 v[2:17], v[154:157], v[158:161], v[2:17]
	v_sub_f32_e32 v227, v234, v223
	v_sub_f32_e32 v228, v234, v224
	v_exp_f32_e32 v227, v227
	v_exp_f32_e32 v228, v228
	v_cmp_ge_i32_e32 vcc, 2, v221
	v_mul_f32_e32 v227, v20, v227
	v_mul_f32_e32 v227, v225, v227
	v_cndmask_b32_e32 v227, 0, v227, vcc
	v_cmp_ge_i32_e32 vcc, 2, v222
	v_mul_f32_e32 v228, v36, v228
	v_mul_f32_e32 v228, v226, v228
	v_cndmask_b32_e32 v228, 0, v228, vcc
	v_cvt_pk_bf16_f32 v227, v227, v228
	ds_write_b16 v220, v227 offset:35360
	ds_write_b16_d16_hi v220, v227 offset:35424
	v_sub_f32_e32 v229, v235, v223
	v_sub_f32_e32 v230, v235, v224
	v_exp_f32_e32 v229, v229
	v_exp_f32_e32 v230, v230
	v_cmp_ge_i32_e32 vcc, 3, v221
	v_mul_f32_e32 v229, v21, v229
	v_mul_f32_e32 v229, v225, v229
	v_cndmask_b32_e32 v229, 0, v229, vcc
	v_cmp_ge_i32_e32 vcc, 3, v222
	v_mul_f32_e32 v230, v37, v230
	v_mul_f32_e32 v230, v226, v230
	v_cndmask_b32_e32 v230, 0, v230, vcc
	v_cvt_pk_bf16_f32 v229, v229, v230
	ds_write_b16 v220, v229 offset:35632
	ds_write_b16_d16_hi v220, v229 offset:35696
	v_mfma_f32_32x32x16_bf16 v[2:17], v[146:149], v[150:153], v[2:17]
	v_sub_f32_e32 v227, v236, v223
	v_sub_f32_e32 v228, v236, v224
	v_exp_f32_e32 v227, v227
	v_exp_f32_e32 v228, v228
	v_cmp_ge_i32_e32 vcc, 8, v221
	v_mul_f32_e32 v227, v22, v227
	v_mul_f32_e32 v227, v225, v227
	v_cndmask_b32_e32 v227, 0, v227, vcc
	v_cmp_ge_i32_e32 vcc, 8, v222
	v_mul_f32_e32 v228, v38, v228
	v_mul_f32_e32 v228, v226, v228
	v_cndmask_b32_e32 v228, 0, v228, vcc
	v_cvt_pk_bf16_f32 v227, v227, v228
	ds_write_b16 v220, v227 offset:36992
	ds_write_b16_d16_hi v220, v227 offset:37056
	v_sub_f32_e32 v229, v237, v223
	v_sub_f32_e32 v230, v237, v224
	v_exp_f32_e32 v229, v229
	v_exp_f32_e32 v230, v230
	v_cmp_ge_i32_e32 vcc, 9, v221
	v_mul_f32_e32 v229, v23, v229
	v_mul_f32_e32 v229, v225, v229
	v_cndmask_b32_e32 v229, 0, v229, vcc
	v_cmp_ge_i32_e32 vcc, 9, v222
	v_mul_f32_e32 v230, v39, v230
	v_mul_f32_e32 v230, v226, v230
	v_cndmask_b32_e32 v230, 0, v230, vcc
	v_cvt_pk_bf16_f32 v229, v229, v230
	ds_write_b16 v220, v229 offset:37264
	ds_write_b16_d16_hi v220, v229 offset:37328
	v_mfma_f32_32x32x16_bf16 v[2:17], v[138:141], v[142:145], v[2:17]
	v_sub_f32_e32 v227, v238, v223
	v_sub_f32_e32 v228, v238, v224
	v_exp_f32_e32 v227, v227
	v_exp_f32_e32 v228, v228
	v_cmp_ge_i32_e32 vcc, 10, v221
	v_mul_f32_e32 v227, v24, v227
	v_mul_f32_e32 v227, v225, v227
	v_cndmask_b32_e32 v227, 0, v227, vcc
	v_cmp_ge_i32_e32 vcc, 10, v222
	v_mul_f32_e32 v228, v40, v228
	v_mul_f32_e32 v228, v226, v228
	v_cndmask_b32_e32 v228, 0, v228, vcc
	v_cvt_pk_bf16_f32 v227, v227, v228
	ds_write_b16 v220, v227 offset:37536
	ds_write_b16_d16_hi v220, v227 offset:37600
	v_sub_f32_e32 v229, v239, v223
	v_sub_f32_e32 v230, v239, v224
	v_exp_f32_e32 v229, v229
	v_exp_f32_e32 v230, v230
	v_cmp_ge_i32_e32 vcc, 11, v221
	v_mul_f32_e32 v229, v25, v229
	v_mul_f32_e32 v229, v225, v229
	v_cndmask_b32_e32 v229, 0, v229, vcc
	v_cmp_ge_i32_e32 vcc, 11, v222
	v_mul_f32_e32 v230, v41, v230
	v_mul_f32_e32 v230, v226, v230
	v_cndmask_b32_e32 v230, 0, v230, vcc
	v_cvt_pk_bf16_f32 v229, v229, v230
	ds_write_b16 v220, v229 offset:37808
	ds_write_b16_d16_hi v220, v229 offset:37872
	v_mfma_f32_32x32x16_bf16 v[2:17], v[130:133], v[134:137], v[2:17]
	v_sub_f32_e32 v227, v172, v223
	v_sub_f32_e32 v228, v172, v224
	v_exp_f32_e32 v227, v227
	v_exp_f32_e32 v228, v228
	v_cmp_ge_i32_e32 vcc, 16, v221
	v_mul_f32_e32 v227, v26, v227
	v_mul_f32_e32 v227, v225, v227
	v_cndmask_b32_e32 v227, 0, v227, vcc
	v_cmp_ge_i32_e32 vcc, 16, v222
	v_mul_f32_e32 v228, v42, v228
	v_mul_f32_e32 v228, v226, v228
	v_cndmask_b32_e32 v228, 0, v228, vcc
	v_cvt_pk_bf16_f32 v227, v227, v228
	ds_write_b16 v220, v227 offset:39168
	ds_write_b16_d16_hi v220, v227 offset:39232
	v_sub_f32_e32 v229, v173, v223
	v_sub_f32_e32 v230, v173, v224
	v_exp_f32_e32 v229, v229
	v_exp_f32_e32 v230, v230
	v_cmp_ge_i32_e32 vcc, 17, v221
	v_mul_f32_e32 v229, v27, v229
	v_mul_f32_e32 v229, v225, v229
	v_cndmask_b32_e32 v229, 0, v229, vcc
	v_cmp_ge_i32_e32 vcc, 17, v222
	v_mul_f32_e32 v230, v43, v230
	v_mul_f32_e32 v230, v226, v230
	v_cndmask_b32_e32 v230, 0, v230, vcc
	v_cvt_pk_bf16_f32 v229, v229, v230
	ds_write_b16 v220, v229 offset:39440
	ds_write_b16_d16_hi v220, v229 offset:39504
	v_mfma_f32_32x32x16_bf16 v[2:17], v[122:125], v[126:129], v[2:17]
	v_sub_f32_e32 v227, v174, v223
	v_sub_f32_e32 v228, v174, v224
	v_exp_f32_e32 v227, v227
	v_exp_f32_e32 v228, v228
	v_cmp_ge_i32_e32 vcc, 18, v221
	v_mul_f32_e32 v227, v28, v227
	v_mul_f32_e32 v227, v225, v227
	v_cndmask_b32_e32 v227, 0, v227, vcc
; __device__ __forceinline__ unsigned short f2bf(float f) { return (unsigned short)(cvt_pk_bf16(f, 0.f) & 0xffffu); }
; __device__ __forceinline__ int crow(int r, int hi) { return (r & 3) + 8 * (r >> 2) + 4 * hi; }
; __device__ __forceinline__ void ssd_item(CArgs a, int layer, int item, LAS unsigned char* lds) {
;     ...
;             const int s0i = 32 * gj0 + r32, s1i = s0i + 32;
;             const float cs0 = v_cs[s0i], cs1 = v_cs[s1i], d0 = v_dt[s0i], d1 = v_dt[s1i];
; #pragma unroll
;             for (int r = 0; r < 16; ++r) {
;                 const int l = 32 * gi + crow(r, hi); const float csl = v_cs[l];
;                 const bool ok0 = dir ? (s0i >= l) : (s0i <= l), ok1 = dir ? (s1i >= l) : (s1i <= l);
;                 const float w0 = ok0 ? G0[r] * __builtin_amdgcn_exp2f(csl - cs0) * d0 : 0.f;
;                 const float w1 = ok1 ? G1[r] * __builtin_amdgcn_exp2f(csl - cs1) * d1 : 0.f;
;                 Bw[l * SS_LD + s0i] = f2bf(w0); Bw[l * SS_LD + s1i] = f2bf(w1);
;             }
	v_cmp_ge_i32_e32 vcc, 18, v222
	v_mul_f32_e32 v228, v44, v228
	v_mul_f32_e32 v228, v226, v228
	v_cndmask_b32_e32 v228, 0, v228, vcc
	v_cvt_pk_bf16_f32 v227, v227, v228
	ds_write_b16 v220, v227 offset:39712
	ds_write_b16_d16_hi v220, v227 offset:39776
	v_sub_f32_e32 v229, v175, v223
	v_sub_f32_e32 v230, v175, v224
	v_exp_f32_e32 v229, v229
	v_exp_f32_e32 v230, v230
	v_cmp_ge_i32_e32 vcc, 19, v221
	v_mul_f32_e32 v229, v29, v229
	v_mul_f32_e32 v229, v225, v229
	v_cndmask_b32_e32 v229, 0, v229, vcc
	v_cmp_ge_i32_e32 vcc, 19, v222
	v_mul_f32_e32 v230, v45, v230
	v_mul_f32_e32 v230, v226, v230
	v_cndmask_b32_e32 v230, 0, v230, vcc
	v_cvt_pk_bf16_f32 v229, v229, v230
	ds_write_b16 v220, v229 offset:39984
	ds_write_b16_d16_hi v220, v229 offset:40048
	v_mfma_f32_32x32x16_bf16 v[2:17], v[114:117], v[118:121], v[2:17]
	v_sub_f32_e32 v227, v178, v223
	v_sub_f32_e32 v228, v178, v224
	v_exp_f32_e32 v227, v227
	v_exp_f32_e32 v228, v228
	v_cmp_ge_i32_e32 vcc, 24, v221
	v_mul_f32_e32 v227, v30, v227
	v_mul_f32_e32 v227, v225, v227
	v_cndmask_b32_e32 v227, 0, v227, vcc
	v_cmp_ge_i32_e32 vcc, 24, v222
	v_mul_f32_e32 v228, v46, v228
	v_mul_f32_e32 v228, v226, v228
	v_cndmask_b32_e32 v228, 0, v228, vcc
	v_cvt_pk_bf16_f32 v227, v227, v228
	ds_write_b16 v220, v227 offset:41344
	ds_write_b16_d16_hi v220, v227 offset:41408
	v_sub_f32_e32 v229, v179, v223
	v_sub_f32_e32 v230, v179, v224
	v_exp_f32_e32 v229, v229
	v_exp_f32_e32 v230, v230
	v_cmp_ge_i32_e32 vcc, 25, v221
	v_mul_f32_e32 v229, v31, v229
	v_mul_f32_e32 v229, v225, v229
	v_cndmask_b32_e32 v229, 0, v229, vcc
	v_cmp_ge_i32_e32 vcc, 25, v222
	v_mul_f32_e32 v230, v47, v230
	v_mul_f32_e32 v230, v226, v230
	v_cndmask_b32_e32 v230, 0, v230, vcc
	v_cvt_pk_bf16_f32 v229, v229, v230
	ds_write_b16 v220, v229 offset:41616
	ds_write_b16_d16_hi v220, v229 offset:41680
	v_mfma_f32_32x32x16_bf16 v[2:17], v[106:109], v[110:113], v[2:17]
	v_sub_f32_e32 v227, v180, v223
	v_sub_f32_e32 v228, v180, v224
	v_exp_f32_e32 v227, v227
	v_exp_f32_e32 v228, v228
	v_cmp_ge_i32_e32 vcc, 26, v221
	v_mul_f32_e32 v227, v32, v227
	v_mul_f32_e32 v227, v225, v227
	v_cndmask_b32_e32 v227, 0, v227, vcc
	v_cmp_ge_i32_e32 vcc, 26, v222
	v_mul_f32_e32 v228, v48, v228
	v_mul_f32_e32 v228, v226, v228
	v_cndmask_b32_e32 v228, 0, v228, vcc
	v_cvt_pk_bf16_f32 v227, v227, v228
	ds_write_b16 v220, v227 offset:41888
	ds_write_b16_d16_hi v220, v227 offset:41952
	v_sub_f32_e32 v229, v181, v223
	v_sub_f32_e32 v230, v181, v224
	v_exp_f32_e32 v229, v229
	v_exp_f32_e32 v230, v230
	v_cmp_ge_i32_e32 vcc, 27, v221
	v_mul_f32_e32 v229, v33, v229
	v_mul_f32_e32 v229, v225, v229
	v_cndmask_b32_e32 v229, 0, v229, vcc
	v_cmp_ge_i32_e32 vcc, 27, v222
	v_mul_f32_e32 v230, v49, v230
	v_mul_f32_e32 v230, v226, v230
	v_cndmask_b32_e32 v230, 0, v230, vcc
	v_cvt_pk_bf16_f32 v229, v229, v230
	ds_write_b16 v220, v229 offset:42160
	ds_write_b16_d16_hi v220, v229 offset:42224
	s_branch .Lssd_w_join
.Lssd_w_bwd:
	v_mfma_f32_32x32x16_bf16 v[2:17], v[162:165], v[166:169], v[2:17]
	v_sub_f32_e32 v227, v232, v223
	v_sub_f32_e32 v228, v232, v224
	v_exp_f32_e32 v227, v227
	v_exp_f32_e32 v228, v228
	v_cmp_le_i32_e32 vcc, 0, v221
	v_mul_f32_e32 v227, v18, v227
	v_mul_f32_e32 v227, v225, v227
	v_cndmask_b32_e32 v227, 0, v227, vcc
	v_cmp_le_i32_e32 vcc, 0, v222
	v_mul_f32_e32 v228, v34, v228
	v_mul_f32_e32 v228, v226, v228
	v_cndmask_b32_e32 v228, 0, v228, vcc
	v_cvt_pk_bf16_f32 v227, v227, v228
	ds_write_b16 v220, v227 offset:34816
	ds_write_b16_d16_hi v220, v227 offset:34880
	v_sub_f32_e32 v229, v233, v223
	v_sub_f32_e32 v230, v233, v224
	v_exp_f32_e32 v229, v229
	v_exp_f32_e32 v230, v230
	v_cmp_le_i32_e32 vcc, 1, v221
	v_mul_f32_e32 v229, v19, v229
	v_mul_f32_e32 v229, v225, v229
	v_cndmask_b32_e32 v229, 0, v229, vcc
	v_cmp_le_i32_e32 vcc, 1, v222
	v_mul_f32_e32 v230, v35, v230
	v_mul_f32_e32 v230, v226, v230
	v_cndmask_b32_e32 v230, 0, v230, vcc
	v_cvt_pk_bf16_f32 v229, v229, v230
	ds_write_b16 v220, v229 offset:35088
	ds_write_b16_d16_hi v220, v229 offset:35152
	v_mfma_f32_32x32x16_bf16 v[2:17], v[154:157], v[158:161], v[2:17]
	v_sub_f32_e32 v227, v234, v223
	v_sub_f32_e32 v228, v234, v224
	v_exp_f32_e32 v227, v227
	v_exp_f32_e32 v228, v228
	v_cmp_le_i32_e32 vcc, 2, v221
	v_mul_f32_e32 v227, v20, v227
	v_mul_f32_e32 v227, v225, v227
	v_cndmask_b32_e32 v227, 0, v227, vcc
	v_cmp_le_i32_e32 vcc, 2, v222
	v_mul_f32_e32 v228, v36, v228
	v_mul_f32_e32 v228, v226, v228
	v_cndmask_b32_e32 v228, 0, v228, vcc
	v_cvt_pk_bf16_f32 v227, v227, v228
	ds_write_b16 v220, v227 offset:35360
	ds_write_b16_d16_hi v220, v227 offset:35424
	v_sub_f32_e32 v229, v235, v223
	v_sub_f32_e32 v230, v235, v224
	v_exp_f32_e32 v229, v229
	v_exp_f32_e32 v230, v230
	v_cmp_le_i32_e32 vcc, 3, v221
	v_mul_f32_e32 v229, v21, v229
	v_mul_f32_e32 v229, v225, v229
	v_cndmask_b32_e32 v229, 0, v229, vcc
	v_cmp_le_i32_e32 vcc, 3, v222
	v_mul_f32_e32 v230, v37, v230
	v_mul_f32_e32 v230, v226, v230
	v_cndmask_b32_e32 v230, 0, v230, vcc
	v_cvt_pk_bf16_f32 v229, v229, v230
	ds_write_b16 v220, v229 offset:35632
	ds_write_b16_d16_hi v220, v229 offset:35696
	v_mfma_f32_32x32x16_bf16 v[2:17], v[146:149], v[150:153], v[2:17]
	v_sub_f32_e32 v227, v236, v223
	v_sub_f32_e32 v228, v236, v224
	v_exp_f32_e32 v227, v227
	v_exp_f32_e32 v228, v228
	v_cmp_le_i32_e32 vcc, 8, v221
	v_mul_f32_e32 v227, v22, v227
	v_mul_f32_e32 v227, v225, v227
	v_cndmask_b32_e32 v227, 0, v227, vcc
	v_cmp_le_i32_e32 vcc, 8, v222
	v_mul_f32_e32 v228, v38, v228
	v_mul_f32_e32 v228, v226, v228
	v_cndmask_b32_e32 v228, 0, v228, vcc
	v_cvt_pk_bf16_f32 v227, v227, v228
	ds_write_b16 v220, v227 offset:36992
	ds_write_b16_d16_hi v220, v227 offset:37056
	v_sub_f32_e32 v229, v237, v223
; __device__ __forceinline__ unsigned short f2bf(float f) { return (unsigned short)(cvt_pk_bf16(f, 0.f) & 0xffffu); }
; __device__ __forceinline__ int crow(int r, int hi) { return (r & 3) + 8 * (r >> 2) + 4 * hi; }
; __device__ __forceinline__ void ssd_item(CArgs a, int layer, int item, LAS unsigned char* lds) {
;     ...
;             const int s0i = 32 * gj0 + r32, s1i = s0i + 32;
;             const float cs0 = v_cs[s0i], cs1 = v_cs[s1i], d0 = v_dt[s0i], d1 = v_dt[s1i];
; #pragma unroll
;             for (int r = 0; r < 16; ++r) {
;                 const int l = 32 * gi + crow(r, hi); const float csl = v_cs[l];
;                 const bool ok0 = dir ? (s0i >= l) : (s0i <= l), ok1 = dir ? (s1i >= l) : (s1i <= l);
;                 const float w0 = ok0 ? G0[r] * __builtin_amdgcn_exp2f(csl - cs0) * d0 : 0.f;
;                 const float w1 = ok1 ? G1[r] * __builtin_amdgcn_exp2f(csl - cs1) * d1 : 0.f;
;                 Bw[l * SS_LD + s0i] = f2bf(w0); Bw[l * SS_LD + s1i] = f2bf(w1);
;             }
	v_sub_f32_e32 v230, v237, v224
	v_exp_f32_e32 v229, v229
	v_exp_f32_e32 v230, v230
	v_cmp_le_i32_e32 vcc, 9, v221
	v_mul_f32_e32 v229, v23, v229
	v_mul_f32_e32 v229, v225, v229
	v_cndmask_b32_e32 v229, 0, v229, vcc
	v_cmp_le_i32_e32 vcc, 9, v222
	v_mul_f32_e32 v230, v39, v230
	v_mul_f32_e32 v230, v226, v230
	v_cndmask_b32_e32 v230, 0, v230, vcc
	v_cvt_pk_bf16_f32 v229, v229, v230
	ds_write_b16 v220, v229 offset:37264
	ds_write_b16_d16_hi v220, v229 offset:37328
	v_mfma_f32_32x32x16_bf16 v[2:17], v[138:141], v[142:145], v[2:17]
	v_sub_f32_e32 v227, v238, v223
	v_sub_f32_e32 v228, v238, v224
	v_exp_f32_e32 v227, v227
	v_exp_f32_e32 v228, v228
	v_cmp_le_i32_e32 vcc, 10, v221
	v_mul_f32_e32 v227, v24, v227
	v_mul_f32_e32 v227, v225, v227
	v_cndmask_b32_e32 v227, 0, v227, vcc
	v_cmp_le_i32_e32 vcc, 10, v222
	v_mul_f32_e32 v228, v40, v228
	v_mul_f32_e32 v228, v226, v228
	v_cndmask_b32_e32 v228, 0, v228, vcc
	v_cvt_pk_bf16_f32 v227, v227, v228
	ds_write_b16 v220, v227 offset:37536
	ds_write_b16_d16_hi v220, v227 offset:37600
	v_sub_f32_e32 v229, v239, v223
	v_sub_f32_e32 v230, v239, v224
	v_exp_f32_e32 v229, v229
	v_exp_f32_e32 v230, v230
	v_cmp_le_i32_e32 vcc, 11, v221
	v_mul_f32_e32 v229, v25, v229
	v_mul_f32_e32 v229, v225, v229
	v_cndmask_b32_e32 v229, 0, v229, vcc
	v_cmp_le_i32_e32 vcc, 11, v222
	v_mul_f32_e32 v230, v41, v230
	v_mul_f32_e32 v230, v226, v230
	v_cndmask_b32_e32 v230, 0, v230, vcc
	v_cvt_pk_bf16_f32 v229, v229, v230
	ds_write_b16 v220, v229 offset:37808
	ds_write_b16_d16_hi v220, v229 offset:37872
	v_mfma_f32_32x32x16_bf16 v[2:17], v[130:133], v[134:137], v[2:17]
	v_sub_f32_e32 v227, v172, v223
	v_sub_f32_e32 v228, v172, v224
	v_exp_f32_e32 v227, v227
	v_exp_f32_e32 v228, v228
	v_cmp_le_i32_e32 vcc, 16, v221
	v_mul_f32_e32 v227, v26, v227
	v_mul_f32_e32 v227, v225, v227
	v_cndmask_b32_e32 v227, 0, v227, vcc
	v_cmp_le_i32_e32 vcc, 16, v222
	v_mul_f32_e32 v228, v42, v228
	v_mul_f32_e32 v228, v226, v228
	v_cndmask_b32_e32 v228, 0, v228, vcc
	v_cvt_pk_bf16_f32 v227, v227, v228
	ds_write_b16 v220, v227 offset:39168
	ds_write_b16_d16_hi v220, v227 offset:39232
	v_sub_f32_e32 v229, v173, v223
	v_sub_f32_e32 v230, v173, v224
	v_exp_f32_e32 v229, v229
	v_exp_f32_e32 v230, v230
	v_cmp_le_i32_e32 vcc, 17, v221
	v_mul_f32_e32 v229, v27, v229
	v_mul_f32_e32 v229, v225, v229
	v_cndmask_b32_e32 v229, 0, v229, vcc
	v_cmp_le_i32_e32 vcc, 17, v222
	v_mul_f32_e32 v230, v43, v230
	v_mul_f32_e32 v230, v226, v230
	v_cndmask_b32_e32 v230, 0, v230, vcc
	v_cvt_pk_bf16_f32 v229, v229, v230
	ds_write_b16 v220, v229 offset:39440
	ds_write_b16_d16_hi v220, v229 offset:39504
	v_mfma_f32_32x32x16_bf16 v[2:17], v[122:125], v[126:129], v[2:17]
	v_sub_f32_e32 v227, v174, v223
	v_sub_f32_e32 v228, v174, v224
	v_exp_f32_e32 v227, v227
	v_exp_f32_e32 v228, v228
	v_cmp_le_i32_e32 vcc, 18, v221
	v_mul_f32_e32 v227, v28, v227
	v_mul_f32_e32 v227, v225, v227
	v_cndmask_b32_e32 v227, 0, v227, vcc
	v_cmp_le_i32_e32 vcc, 18, v222
	v_mul_f32_e32 v228, v44, v228
	v_mul_f32_e32 v228, v226, v228
	v_cndmask_b32_e32 v228, 0, v228, vcc
	v_cvt_pk_bf16_f32 v227, v227, v228
	ds_write_b16 v220, v227 offset:39712
	ds_write_b16_d16_hi v220, v227 offset:39776
	v_sub_f32_e32 v229, v175, v223
	v_sub_f32_e32 v230, v175, v224
	v_exp_f32_e32 v229, v229
	v_exp_f32_e32 v230, v230
	v_cmp_le_i32_e32 vcc, 19, v221
	v_mul_f32_e32 v229, v29, v229
	v_mul_f32_e32 v229, v225, v229
	v_cndmask_b32_e32 v229, 0, v229, vcc
	v_cmp_le_i32_e32 vcc, 19, v222
	v_mul_f32_e32 v230, v45, v230
	v_mul_f32_e32 v230, v226, v230
	v_cndmask_b32_e32 v230, 0, v230, vcc
	v_cvt_pk_bf16_f32 v229, v229, v230
	ds_write_b16 v220, v229 offset:39984
	ds_write_b16_d16_hi v220, v229 offset:40048
	v_mfma_f32_32x32x16_bf16 v[2:17], v[114:117], v[118:121], v[2:17]
	v_sub_f32_e32 v227, v178, v223
	v_sub_f32_e32 v228, v178, v224
	v_exp_f32_e32 v227, v227
	v_exp_f32_e32 v228, v228
	v_cmp_le_i32_e32 vcc, 24, v221
	v_mul_f32_e32 v227, v30, v227
	v_mul_f32_e32 v227, v225, v227
	v_cndmask_b32_e32 v227, 0, v227, vcc
	v_cmp_le_i32_e32 vcc, 24, v222
	v_mul_f32_e32 v228, v46, v228
	v_mul_f32_e32 v228, v226, v228
	v_cndmask_b32_e32 v228, 0, v228, vcc
	v_cvt_pk_bf16_f32 v227, v227, v228
	ds_write_b16 v220, v227 offset:41344
	ds_write_b16_d16_hi v220, v227 offset:41408
	v_sub_f32_e32 v229, v179, v223
	v_sub_f32_e32 v230, v179, v224
	v_exp_f32_e32 v229, v229
	v_exp_f32_e32 v230, v230
	v_cmp_le_i32_e32 vcc, 25, v221
	v_mul_f32_e32 v229, v31, v229
	v_mul_f32_e32 v229, v225, v229
	v_cndmask_b32_e32 v229, 0, v229, vcc
	v_cmp_le_i32_e32 vcc, 25, v222
	v_mul_f32_e32 v230, v47, v230
	v_mul_f32_e32 v230, v226, v230
	v_cndmask_b32_e32 v230, 0, v230, vcc
	v_cvt_pk_bf16_f32 v229, v229, v230
	ds_write_b16 v220, v229 offset:41616
	ds_write_b16_d16_hi v220, v229 offset:41680
	v_mfma_f32_32x32x16_bf16 v[2:17], v[106:109], v[110:113], v[2:17]
	v_sub_f32_e32 v227, v180, v223
	v_sub_f32_e32 v228, v180, v224
	v_exp_f32_e32 v227, v227
	v_exp_f32_e32 v228, v228
	v_cmp_le_i32_e32 vcc, 26, v221
	v_mul_f32_e32 v227, v32, v227
	v_mul_f32_e32 v227, v225, v227
	v_cndmask_b32_e32 v227, 0, v227, vcc
	v_cmp_le_i32_e32 vcc, 26, v222
	v_mul_f32_e32 v228, v48, v228
	v_mul_f32_e32 v228, v226, v228
	v_cndmask_b32_e32 v228, 0, v228, vcc
	v_cvt_pk_bf16_f32 v227, v227, v228
	ds_write_b16 v220, v227 offset:41888
	ds_write_b16_d16_hi v220, v227 offset:41952
	v_sub_f32_e32 v229, v181, v223
	v_sub_f32_e32 v230, v181, v224
	v_exp_f32_e32 v229, v229
	v_exp_f32_e32 v230, v230
	v_cmp_le_i32_e32 vcc, 27, v221
	v_mul_f32_e32 v229, v33, v229
	v_mul_f32_e32 v229, v225, v229
	v_cndmask_b32_e32 v229, 0, v229, vcc
	v_cmp_le_i32_e32 vcc, 27, v222
	v_mul_f32_e32 v230, v49, v230
	v_mul_f32_e32 v230, v226, v230
	v_cndmask_b32_e32 v230, 0, v230, vcc
	v_cvt_pk_bf16_f32 v229, v229, v230
	ds_write_b16 v220, v229 offset:42160
	ds_write_b16_d16_hi v220, v229 offset:42224
; #define LAS __attribute__((address_space(3)))
; __device__ __forceinline__ float bf2f(unsigned short h) { return __uint_as_float((unsigned)h << 16); }
; __device__ __forceinline__ unsigned short f2bf(float f) { return (unsigned short)(cvt_pk_bf16(f, 0.f) & 0xffffu); }
; #define MFMA32(a, b, c) __builtin_amdgcn_mfma_f32_32x32x16_bf16((a), (b), (c), 0, 0, 0)
; __device__ __forceinline__ int crow(int r, int hi) { return (r & 3) + 8 * (r >> 2) + 4 * hi; }
; __device__ __forceinline__ void ssd_item(CArgs a, int layer, int item, LAS unsigned char* lds) {
;     ...
;             const int s0i = 32 * gj0 + r32, s1i = s0i + 32;
;             const float cs0 = v_cs[s0i], cs1 = v_cs[s1i], d0 = v_dt[s0i], d1 = v_dt[s1i];
; #pragma unroll
;             for (int r = 0; r < 16; ++r) {
;                 const int l = 32 * gi + crow(r, hi); const float csl = v_cs[l];
;                 const bool ok0 = dir ? (s0i >= l) : (s0i <= l), ok1 = dir ? (s1i >= l) : (s1i <= l);
;                 const float w0 = ok0 ? G0[r] * __builtin_amdgcn_exp2f(csl - cs0) * d0 : 0.f;
;                 const float w1 = ok1 ? G1[r] * __builtin_amdgcn_exp2f(csl - cs1) * d1 : 0.f;
;                 Bw[l * SS_LD + s0i] = f2bf(w0); Bw[l * SS_LD + s1i] = f2bf(w1);
;             }
;         }
;         __syncthreads();
;         float yv[16];
;         {
;             f32x16 Yd, Yo;
; #pragma unroll
;             for (int r = 0; r < 16; ++r) { Yd[r] = 0.f; Yo[r] = 0.f; }
; #pragma unroll
;             for (int ks = 0; ks < 8; ++ks) {
;                 const bf16x8 wa = *(const LAS bf16x8*)(Bw + (32 * yi + r32) * SS_LD + 16 * ks + 8 * hi);
;                 const bf16x8 xb = *(const LAS bf16x8*)(Xt + (32 * yj + r32) * SS_LD + 16 * ks + 8 * hi);
;                 Yd = MFMA32(wa, xb, Yd);
;                 const bf16x8 ca = *(const LAS bf16x8*)(Cm + (32 * yi + r32) * SS_LD + 16 * ks + 8 * hi);
;                 const bf16x8 sb = *(const LAS bf16x8*)(Sb + (32 * yj + r32) * SS_LD + 16 * ks + 8 * hi);
;                 Yo = MFMA32(ca, sb, Yo);
;             }
;             const int p = 32 * yj + r32;
; #pragma unroll
;             for (int r = 0; r < 16; ++r) {
;                 const int l = 32 * yi + crow(r, hi);
;                 float y = Yd[r] + v_ecs[l] * Yo[r];
;                 y += Dh * bf2f(Xt[p * SS_LD + l]);
;                 yv[r] = y;
;             }
.Lssd_w_join:
	v_or_b32_e32 v199, 8, v182
	v_lshlrev_b32_e32 v189, 2, v199
	v_lshl_or_b32 v114, s27, 5, v0
	s_lshl_b32 s27, s3, 7
	v_or_b32_e32 v37, 24, v182
	s_add_i32 s3, 0, 0x22400
	v_lshlrev_b32_e32 v0, 1, v0
	s_cmp_lg_u32 s10, -2
	v_lshlrev_b32_e32 v171, 2, v37
	v_or_b32_e32 v18, 16, v182
	v_lshlrev_b32_e32 v170, 2, v18
	v_mul_u32_u24_e32 v22, 0x88, v114
	v_lshlrev_b32_e32 v38, 1, v22
	v_add3_u32 v115, s38, v38, v194
	v_add3_u32 v140, s75, v38, v194
	s_waitcnt lgkmcnt(0)
	s_barrier
	ds_read_b128 v[18:21], v193 offset:34816
	ds_read_b128 v[22:25], v115
	ds_read_b128 v[116:119], v115 offset:32
	ds_read_b128 v[120:123], v193 offset:34848
	ds_read_b128 v[34:37], v193
	s_waitcnt lgkmcnt(3)
	v_mfma_f32_32x32x16_bf16 v[18:33], v[18:21], v[22:25], 0
	ds_read_b128 v[38:41], v140
	ds_read_b128 v[124:127], v193 offset:32
	ds_read_b128 v[128:131], v140 offset:32
	s_waitcnt lgkmcnt(2)
	v_mfma_f32_32x32x16_bf16 v[34:49], v[34:37], v[38:41], 0
	v_mfma_f32_32x32x16_bf16 v[18:33], v[120:123], v[116:119], v[18:33]
	s_waitcnt lgkmcnt(0)
	v_mfma_f32_32x32x16_bf16 v[34:49], v[124:127], v[128:131], v[34:49]
	ds_read_b128 v[116:119], v193 offset:34880
	ds_read_b128 v[120:123], v115 offset:64
	ds_read_b128 v[124:127], v193 offset:34912
	ds_read_b128 v[128:131], v115 offset:96
	s_waitcnt lgkmcnt(2)
	v_mfma_f32_32x32x16_bf16 v[18:33], v[116:119], v[120:123], v[18:33]
	ds_read_b128 v[116:119], v193 offset:64
	ds_read_b128 v[120:123], v140 offset:64
	ds_read_b128 v[132:135], v193 offset:96
	ds_read_b128 v[136:139], v140 offset:96
	s_waitcnt lgkmcnt(2)
	v_mfma_f32_32x32x16_bf16 v[34:49], v[116:119], v[120:123], v[34:49]
	v_mfma_f32_32x32x16_bf16 v[18:33], v[124:127], v[128:131], v[18:33]
	ds_read_b128 v[116:119], v193 offset:34944
	ds_read_b128 v[120:123], v115 offset:128
	ds_read_b128 v[124:127], v193 offset:34976
	ds_read_b128 v[128:131], v115 offset:160
	s_waitcnt lgkmcnt(4)
	v_mfma_f32_32x32x16_bf16 v[34:49], v[132:135], v[136:139], v[34:49]
	s_waitcnt lgkmcnt(2)
	v_mfma_f32_32x32x16_bf16 v[18:33], v[116:119], v[120:123], v[18:33]
	ds_read_b128 v[116:119], v193 offset:128
	ds_read_b128 v[120:123], v140 offset:128
	ds_read_b128 v[132:135], v193 offset:160
	ds_read_b128 v[136:139], v140 offset:160
	s_waitcnt lgkmcnt(2)
	v_mfma_f32_32x32x16_bf16 v[34:49], v[116:119], v[120:123], v[34:49]
	v_mfma_f32_32x32x16_bf16 v[18:33], v[124:127], v[128:131], v[18:33]
	ds_read_b128 v[116:119], v193 offset:35008
	ds_read_b128 v[120:123], v115 offset:192
	ds_read_b128 v[124:127], v193 offset:35040
	ds_read_b128 v[128:131], v115 offset:224
	v_mul_u32_u24_e32 v115, 0x110, v114
	s_waitcnt lgkmcnt(4)
	v_mfma_f32_32x32x16_bf16 v[34:49], v[132:135], v[136:139], v[34:49]
	s_waitcnt lgkmcnt(2)
	v_mfma_f32_32x32x16_bf16 v[18:33], v[116:119], v[120:123], v[18:33]
	ds_read_b128 v[116:119], v193 offset:192
	ds_read_b128 v[120:123], v140 offset:192
	ds_read_b128 v[132:135], v193 offset:224
	ds_read_b128 v[136:139], v140 offset:224
	s_waitcnt lgkmcnt(2)
	v_mfma_f32_32x32x16_bf16 v[34:49], v[116:119], v[120:123], v[34:49]
	v_lshlrev_b32_e32 v120, 1, v182
	v_add3_u32 v115, s38, v115, v120
	ds_read2_b64 v[120:123], v115 offset1:2
	v_add_u32_e32 v116, s3, v184
	ds_read_b128 v[116:119], v116
	v_mfma_f32_32x32x16_bf16 v[18:33], v[124:127], v[128:131], v[18:33]
	v_add_u32_e32 v124, s3, v189
	ds_read_b128 v[124:127], v124
	ds_read2_b64 v[128:131], v115 offset0:4 offset1:6
	s_waitcnt lgkmcnt(4)
	v_mfma_f32_32x32x16_bf16 v[34:49], v[132:135], v[136:139], v[34:49]
	s_waitcnt lgkmcnt(1)
	s_nop 10
	v_fma_f32 v38, v38, v124, v22
	v_fma_f32 v41, v41, v127, v25
	v_and_b32_e32 v22, 0xffff0000, v123
	v_fmac_f32_e32 v41, v190, v22
	v_add_u32_e32 v22, s3, v171
	v_fma_f32 v39, v39, v125, v23
	v_fma_f32 v40, v40, v126, v24
	ds_read_b128 v[22:25], v22
	v_fma_f32 v34, v34, v116, v18
	v_lshlrev_b32_e32 v18, 16, v120
	v_fmac_f32_e32 v34, v190, v18
	v_fma_f32 v35, v35, v117, v19
	v_and_b32_e32 v18, 0xffff0000, v120
	v_fmac_f32_e32 v35, v190, v18
	v_fma_f32 v36, v36, v118, v20
	v_lshlrev_b32_e32 v18, 16, v121
	v_fmac_f32_e32 v36, v190, v18
	v_fma_f32 v37, v37, v119, v21
	v_and_b32_e32 v18, 0xffff0000, v121
	v_fmac_f32_e32 v37, v190, v18
	v_lshlrev_b32_e32 v18, 16, v122
	s_waitcnt lgkmcnt(0)
	v_fmac_f32_e32 v33, v49, v25
	v_and_b32_e32 v25, 0xffff0000, v131
	v_fmac_f32_e32 v38, v190, v18
	v_and_b32_e32 v18, 0xffff0000, v122
	v_fmac_f32_e32 v33, v190, v25
	v_or_b32_e32 v25, s34, v183
	v_fmac_f32_e32 v39, v190, v18
	v_lshlrev_b32_e32 v18, 16, v123
	v_mul_lo_u32 v25, v25, s84
	v_fmac_f32_e32 v40, v190, v18
	v_add_u32_e32 v18, s3, v170
	v_add3_u32 v0, s2, v0, v25
	v_cvt_pk_bf16_f32 v25, v3, s0
	ds_read_b128 v[18:21], v18
	s_waitcnt lgkmcnt(0)
	s_barrier
; __device__ __forceinline__ float bf2f(unsigned short h) { return __uint_as_float((unsigned)h << 16); }
; __device__ __forceinline__ unsigned short f2bf(float f) { return (unsigned short)(cvt_pk_bf16(f, 0.f) & 0xffffu); }
; __device__ __forceinline__ int crow(int r, int hi) { return (r & 3) + 8 * (r >> 2) + 4 * hi; }
; __device__ __forceinline__ void ssd_item(CArgs a, int layer, int item, LAS unsigned char* lds) {
;     ...
;             const int p = 32 * yj + r32;
; #pragma unroll
;             for (int r = 0; r < 16; ++r) {
;                 const int l = 32 * yi + crow(r, hi);
;                 float y = Yd[r] + v_ecs[l] * Yo[r];
;                 y += Dh * bf2f(Xt[p * SS_LD + l]);
;                 yv[r] = y;
;             }
;         }
;         __syncthreads();
;         {
;             const int n = 32 * sj + r32;
; #pragma unroll
;             for (int r = 0; r < 16; ++r) Sb[(32 * si + crow(r, hi)) * SS_LD + n] = f2bf(Sacc[r]);
;             const int p = 32 * yj + r32;
; #pragma unroll
;             for (int r = 0; r < 16; ++r) Bw[(32 * yi + crow(r, hi)) * YS_LD + p] = f2bf(yv[r]);
;         }
;         tprev = t0;
	ds_write_b16 v0, v25 offset:272
	v_cvt_pk_bf16_f32 v25, v4, s0
	ds_write_b16 v0, v25 offset:544
	v_cvt_pk_bf16_f32 v25, v5, s0
	ds_write_b16 v0, v25 offset:816
	v_cvt_pk_bf16_f32 v25, v6, s0
	ds_write_b16 v0, v25 offset:2176
	v_cvt_pk_bf16_f32 v25, v7, s0
	ds_write_b16 v0, v25 offset:2448
	v_cvt_pk_bf16_f32 v25, v8, s0
	ds_write_b16 v0, v25 offset:2720
	v_cvt_pk_bf16_f32 v25, v9, s0
	v_fma_f32 v18, v42, v18, v26
	v_lshlrev_b32_e32 v26, 16, v128
	ds_write_b16 v0, v25 offset:2992
	v_cvt_pk_bf16_f32 v25, v10, s0
	v_fmac_f32_e32 v18, v190, v26
	v_fma_f32 v19, v43, v19, v27
	v_and_b32_e32 v26, 0xffff0000, v128
	ds_write_b16 v0, v25 offset:4352
	v_cvt_pk_bf16_f32 v25, v11, s0
	v_fmac_f32_e32 v19, v190, v26
	v_fma_f32 v20, v44, v20, v28
	v_lshlrev_b32_e32 v26, 16, v129
	ds_write_b16 v0, v25 offset:4624
	v_cvt_pk_bf16_f32 v25, v12, s0
	v_fmac_f32_e32 v20, v190, v26
	v_fma_f32 v21, v45, v21, v29
	v_and_b32_e32 v26, 0xffff0000, v129
	ds_write_b16 v0, v25 offset:4896
	v_cvt_pk_bf16_f32 v25, v13, s0
	v_fmac_f32_e32 v21, v190, v26
	v_fma_f32 v22, v46, v22, v30
	v_lshlrev_b32_e32 v26, 16, v130
	ds_write_b16 v0, v25 offset:5168
	v_cvt_pk_bf16_f32 v25, v14, s0
	v_fmac_f32_e32 v22, v190, v26
	v_fma_f32 v23, v47, v23, v31
	v_and_b32_e32 v26, 0xffff0000, v130
	ds_write_b16 v0, v25 offset:6528
	v_cvt_pk_bf16_f32 v25, v15, s0
	v_fmac_f32_e32 v23, v190, v26
	v_fma_f32 v24, v48, v24, v32
	v_lshlrev_b32_e32 v26, 16, v131
	ds_write_b16 v0, v25 offset:6800
	v_cvt_pk_bf16_f32 v25, v16, s0
	v_fmac_f32_e32 v24, v190, v26
	v_cvt_pk_bf16_f32 v26, v2, s0
	ds_write_b16 v0, v25 offset:7072
	v_cvt_pk_bf16_f32 v25, v17, s0
	ds_write_b16 v0, v26
	ds_write_b16 v0, v25 offset:7344
	v_lshlrev_b32_e32 v0, 1, v114
	v_mul_lo_u32 v26, v182, s82
	v_cvt_pk_bf16_f32 v25, v34, s0
	v_add3_u32 v0, 0, v0, v26
	v_cvt_pk_bf16_f32 v18, v18, s0
	ds_write_b16 v0, v25 offset:34816
	v_cvt_pk_bf16_f32 v25, v35, s0
	ds_write_b16 v0, v18 offset:37120
	v_cvt_pk_bf16_f32 v18, v19, s0
	ds_write_b16 v0, v25 offset:34960
	v_cvt_pk_bf16_f32 v25, v36, s0
	ds_write_b16 v0, v18 offset:37264
	v_cvt_pk_bf16_f32 v18, v20, s0
	ds_write_b16 v0, v25 offset:35104
	v_cvt_pk_bf16_f32 v25, v37, s0
	ds_write_b16 v0, v18 offset:37408
	v_cvt_pk_bf16_f32 v18, v21, s0
	ds_write_b16 v0, v25 offset:35248
	v_cvt_pk_bf16_f32 v25, v38, s0
	ds_write_b16 v0, v18 offset:37552
	v_cvt_pk_bf16_f32 v18, v22, s0
	ds_write_b16 v0, v25 offset:35968
	v_cvt_pk_bf16_f32 v25, v39, s0
	ds_write_b16 v0, v18 offset:38272
	v_cvt_pk_bf16_f32 v18, v23, s0
	ds_write_b16 v0, v25 offset:36112
	v_cvt_pk_bf16_f32 v25, v40, s0
	ds_write_b16 v0, v18 offset:38416
	v_cvt_pk_bf16_f32 v18, v24, s0
	ds_write_b16 v0, v25 offset:36256
	v_cvt_pk_bf16_f32 v25, v41, s0
	ds_write_b16 v0, v18 offset:38560
	v_cvt_pk_bf16_f32 v18, v33, s0
	ds_write_b16 v0, v25 offset:36400
	ds_write_b16 v0, v18 offset:38704
	s_cbranch_scc0 .LBB0_177
	s_mov_b32 s90, s26
	s_branch .LBB0_196
